# attention loops: 32 v_mov_b32 per key tile merged into 16 v_pk_mov_b32
# baseline (speedup 1.0000x reference)
; DI void attn_item(const Params& p, int item, char* smem) {
;     ...
; #pragma unroll 1
;     for (int i = i0; i < 9; ++i) {
;       const int k0 = kbase + 64 * i;
;       kv_commit(kvr, Ks, Vts, tid);
;       if (i + 1 < 9) kv_issue(kvr, KW + ((size_t)(b * 4096 + k0 + 64)) * 128 + g * 64, 128, VTW + (size_t)bg * 64 * 4096 + k0 + 64, 4096, tid);
;       if (i >= 1 && i <= 7) attend_tile<1, false, 0, 0>(Ks, Vts, qf, O, m, l, t - k0, slope2, true, 0.f, nullptr, 0, lr, hh);
;       else attend_tile<1, true, 1, 0>(Ks, Vts, qf, O, m, l, t - k0, slope2, true, 0.f, nullptr, 0, lr, hh);
;       pb ^= 1;
;     }
.LBB0_626:
	s_add_i32 s0, s89, 1
	s_xor_b32 s79, s79, 1
	s_cmp_gt_u32 s89, 7
	s_cbranch_scc1 .LBB0_648
	v_mov_b32_e32 v142, v146
	s_mov_b32 s89, s0
	v_mov_b32_e32 v143, v145
	s_nop 0
	v_pk_mov_b32 v[108:109], v[16:17], v[16:17] op_sel:[0,1]
	v_pk_mov_b32 v[110:111], v[18:19], v[18:19] op_sel:[0,1]
	v_pk_mov_b32 v[112:113], v[20:21], v[20:21] op_sel:[0,1]
	v_pk_mov_b32 v[114:115], v[22:23], v[22:23] op_sel:[0,1]
	v_pk_mov_b32 v[118:119], v[24:25], v[24:25] op_sel:[0,1]
	v_pk_mov_b32 v[120:121], v[26:27], v[26:27] op_sel:[0,1]
	v_pk_mov_b32 v[122:123], v[28:29], v[28:29] op_sel:[0,1]
	v_pk_mov_b32 v[124:125], v[30:31], v[30:31] op_sel:[0,1]
	v_pk_mov_b32 v[132:133], v[0:1], v[0:1] op_sel:[0,1]
	v_pk_mov_b32 v[134:135], v[2:3], v[2:3] op_sel:[0,1]
	v_pk_mov_b32 v[138:139], v[4:5], v[4:5] op_sel:[0,1]
	v_pk_mov_b32 v[126:127], v[6:7], v[6:7] op_sel:[0,1]
	v_pk_mov_b32 v[128:129], v[8:9], v[8:9] op_sel:[0,1]
	v_pk_mov_b32 v[130:131], v[10:11], v[10:11] op_sel:[0,1]
	v_pk_mov_b32 v[136:137], v[12:13], v[12:13] op_sel:[0,1]
	v_pk_mov_b32 v[140:141], v[14:15], v[14:15] op_sel:[0,1]
	s_branch .LBB0_612

; DI void attn_item(const Params& p, int item, char* smem) {
;     ...
; #pragma unroll 1
;     while (j >= 0) {
;       kv_commit(kvr, Ks, Vts, tid);
;       int jn = -1;
;       if (am) { jn = __builtin_ctzll(am); am &= am - 1; }
;       if (jn >= 0) kv_issue(kvr, KS + ((size_t)(b * 4096 + 64 * jn)) * 128 + g * 64, 128, VTS + (size_t)bg * 64 * 4096 + 64 * jn, 4096, tid);
;       bool ls = (j < 32) ? ((mylo >> j) & 1u) : ((myhi >> (j - 32)) & 1u);
;       if (j < qb) attend_tile<1, false, 2, 0>(Ks, Vts, qf, O, m, l, t - 64 * j, slope2, ls, 0.f, nullptr, 0, lr, hh);
;       else attend_tile<1, false, 1, 0>(Ks, Vts, qf, O, m, l, t - 64 * j, slope2, ls, 0.f, nullptr, 0, lr, hh);
;       pb ^= 1;
;       j = jn;
;     }
.LBB0_646:
	s_add_u32 s0, s88, -1
	s_addc_u32 s1, s89, -1
	s_and_b64 s[88:89], s[0:1], s[88:89]
	s_andn2_b64 vcc, exec, s[90:91]
	s_xor_b32 s79, s79, 1
	s_cbranch_vccz .LBB0_611
	v_mov_b32_e32 v168, v167
	s_mov_b32 s80, s92
	v_mov_b32_e32 v169, v166
	v_pk_mov_b32 v[122:123], v[16:17], v[16:17] op_sel:[0,1]
	v_pk_mov_b32 v[124:125], v[18:19], v[18:19] op_sel:[0,1]
	v_pk_mov_b32 v[126:127], v[20:21], v[20:21] op_sel:[0,1]
	v_pk_mov_b32 v[128:129], v[22:23], v[22:23] op_sel:[0,1]
	v_pk_mov_b32 v[130:131], v[24:25], v[24:25] op_sel:[0,1]
	v_pk_mov_b32 v[132:133], v[26:27], v[26:27] op_sel:[0,1]
	v_pk_mov_b32 v[134:135], v[28:29], v[28:29] op_sel:[0,1]
	v_pk_mov_b32 v[136:137], v[30:31], v[30:31] op_sel:[0,1]
	v_pk_mov_b32 v[138:139], v[0:1], v[0:1] op_sel:[0,1]
	v_pk_mov_b32 v[140:141], v[2:3], v[2:3] op_sel:[0,1]
	v_pk_mov_b32 v[142:143], v[4:5], v[4:5] op_sel:[0,1]
	v_pk_mov_b32 v[144:145], v[6:7], v[6:7] op_sel:[0,1]
	v_pk_mov_b32 v[146:147], v[8:9], v[8:9] op_sel:[0,1]
	v_pk_mov_b32 v[148:149], v[10:11], v[10:11] op_sel:[0,1]
	v_pk_mov_b32 v[150:151], v[12:13], v[12:13] op_sel:[0,1]
	v_pk_mov_b32 v[152:153], v[14:15], v[14:15] op_sel:[0,1]
	s_branch .LBB0_631
